# weight transposes (inputs only) moved from the end of phase 1 into the barrier-1 wait window
# speedup vs baseline: 1.0055x; 1.0055x over previous
.Lrope_done:
	s_or_b64 exec, exec, s[20:21]
	v_writelane_b32 v253, s2, 0
	v_writelane_b32 v253, s3, 1
	v_and_b32_e32 v208, 63, v0
	v_and_b32_e32 v12, 31, v0
	v_lshlrev_b32_e32 v202, 3, v208
	v_readfirstlane_b32 s0, v0
	s_ashr_i32 s28, s0, 6
	s_lshl_b32 s29, s64, 3
	s_add_i32 s0, s28, s29
	v_readlane_b32 s1, v254, 2
	s_nop 3
	s_lshl_b32 s1, s1, 3

.LBB0_115:
	s_waitcnt vmcnt(4)
	ds_write_b32 v110, v100
	ds_write_b32 v110, v101 offset:264
	ds_write_b32 v110, v102 offset:528
	ds_write_b32 v110, v103 offset:792
	ds_write_b32 v110, v104 offset:1056
	ds_write_b32 v110, v105 offset:1320
	ds_write_b32 v110, v106 offset:1584
	ds_write_b32 v110, v107 offset:1848
	s_waitcnt lgkmcnt(0)
	ds_read_b32 v112, v111
	ds_read_b32 v113, v111 offset:132
	ds_read_b32 v114, v111 offset:264
	ds_read_b32 v115, v111 offset:396
	ds_read_b32 v116, v111 offset:528
	ds_read_b32 v117, v111 offset:660
	ds_read_b32 v118, v111 offset:792
	ds_read_b32 v119, v111 offset:924
	s_waitcnt lgkmcnt(0)
	v_cvt_pk_bf16_f32 v120, v112, v113
	v_cvt_pk_bf16_f32 v121, v114, v115
	v_cvt_pk_bf16_f32 v122, v116, v117
	v_cvt_pk_bf16_f32 v123, v118, v119
	s_add_u32 s100, s82, 0x900000
	s_addc_u32 s101, s83, 0
	global_store_dwordx4 v124, v[120:123], s[100:101]
	v_mov_b32_e32 v2, v12
	v_readlane_b32 s2, v253, 0
	v_readlane_b32 s3, v253, 1
	s_mov_b64 s[20:21], exec
	v_readlane_b32 s22, v254, 6
	s_nop 3
	s_mov_b32 exec_lo, s22
	s_mov_b32 exec_hi, 0
	s_cbranch_execz .Lsplit1_join
	v_mov_b32_e32 v240, 0x7000
	v_mov_b32_e32 v242, 0

.LBB0_98:
	s_waitcnt vmcnt(7) lgkmcnt(7)
	v_pk_mul_f32 v[214:215], v[184:185], v[184:185]
	s_waitcnt lgkmcnt(6)
	v_pk_mul_f32 v[216:217], v[182:183], v[182:183]
	s_waitcnt vmcnt(4)
	v_mul_f32_e32 v213, v190, v190
	s_waitcnt lgkmcnt(5)
	v_pk_mov_b32 v[218:219], v[216:217], v[214:215] op_sel:[1,0]
	v_mov_b32_e32 v217, v215
	v_pk_add_f32 v[214:215], v[218:219], v[216:217]
	v_pk_mul_f32 v[216:217], v[176:177], v[176:177]
	v_pk_mul_f32 v[218:219], v[174:175], v[174:175]
	v_pk_add_f32 v[214:215], v[214:215], v[214:215] op_sel:[0,1] op_sel_hi:[1,0]
	s_waitcnt lgkmcnt(4)
	v_pk_mov_b32 v[220:221], v[218:219], v[216:217] op_sel:[1,0]
	v_mov_b32_e32 v219, v217
	v_pk_add_f32 v[216:217], v[220:221], v[218:219]
	v_mul_f32_e32 v218, v191, v191
	v_pk_add_f32 v[216:217], v[216:217], v[216:217] op_sel:[0,1] op_sel_hi:[1,0]
	v_mov_b32_e32 v215, v213
	v_mov_b32_e32 v217, v218
	v_pk_add_f32 v[214:215], v[214:215], v[216:217]
	v_mul_f32_e32 v216, v195, v195
	v_mul_f32_e32 v219, v192, v192
	v_pk_fma_f32 v[216:217], v[194:195], v[194:195], v[216:217] op_sel_hi:[1,1,0]
	v_mul_f32_e32 v218, v197, v197
	v_mul_f32_e32 v220, v193, v193
	v_mov_b32_e32 v217, v219
	v_pk_fma_f32 v[218:219], v[196:197], v[196:197], v[218:219] op_sel_hi:[1,1,0]
	s_ashr_i32 s13, s12, 31
	v_mov_b32_e32 v219, v220
	v_pk_add_f32 v[216:217], v[216:217], v[218:219]
	s_lshl_b64 s[4:5], s[12:13], 11
	v_pk_add_f32 v[214:215], v[214:215], v[216:217]
	s_nop 0
	v_add_f32_e32 v213, v214, v215
	s_nop 1
	v_add_f32_dpp v213, v213, v213 quad_perm:[1,0,3,2] row_mask:0xf bank_mask:0xf bound_ctrl:1
	s_nop 1
	v_add_f32_dpp v213, v213, v213 quad_perm:[2,3,0,1] row_mask:0xf bank_mask:0xf bound_ctrl:1
	s_nop 1
	v_add_f32_dpp v213, v213, v213 row_half_mirror row_mask:0xf bank_mask:0xf bound_ctrl:1
	s_nop 1
	v_add_f32_dpp v213, v213, v213 row_mirror row_mask:0xf bank_mask:0xf bound_ctrl:1
	ds_bpermute_b32 v214, v200, v213
	s_waitcnt lgkmcnt(0)
	v_add_f32_e32 v213, v213, v214
	ds_bpermute_b32 v214, v203, v213
	s_waitcnt lgkmcnt(0)
	v_add_f32_e32 v213, v213, v214
	v_fmamk_f32 v213, v213, 0x3a800000, v211
	v_rsq_f32_e32 v230, v213
	ds_read_b128 v[214:217], v210
	ds_read_b128 v[218:221], v210 offset:4096
	ds_read_b128 v[222:225], v210 offset:1024
	ds_read_b128 v[226:229], v210 offset:5120
	v_pk_mul_f32 v[182:183], v[182:183], v[230:231] op_sel_hi:[1,0]
	v_pk_mul_f32 v[184:185], v[184:185], v[230:231] op_sel_hi:[1,0]
	s_waitcnt lgkmcnt(2)
	v_pk_fma_f32 v[182:183], v[214:215], v[182:183], v[218:219]
	v_pk_fma_f32 v[184:185], v[216:217], v[184:185], v[220:221]
	ds_read_b128 v[214:217], v210 offset:2048
	ds_read_b128 v[218:221], v210 offset:6144
	v_pk_mul_f32 v[174:175], v[174:175], v[230:231] op_sel_hi:[1,0]
	v_pk_mul_f32 v[176:177], v[176:177], v[230:231] op_sel_hi:[1,0]
	s_waitcnt lgkmcnt(2)
	v_pk_fma_f32 v[174:175], v[222:223], v[174:175], v[226:227]
	v_pk_fma_f32 v[176:177], v[224:225], v[176:177], v[228:229]
	ds_read_b128 v[222:225], v210 offset:3072
	ds_read_b128 v[226:229], v210 offset:7168
	v_pk_mul_f32 v[194:195], v[194:195], v[230:231] op_sel_hi:[1,0]
	v_pk_mul_f32 v[196:197], v[196:197], v[230:231] op_sel_hi:[1,0]
	s_waitcnt lgkmcnt(2)
	v_pk_fma_f32 v[194:195], v[214:215], v[194:195], v[218:219]
	v_pk_fma_f32 v[196:197], v[216:217], v[196:197], v[220:221]
	v_lshl_add_u64 v[214:215], v[206:207], 0, s[4:5]
	v_cvt_pk_bf16_f32 v216, v182, v183
	v_cvt_pk_bf16_f32 v217, v184, v185
	v_pk_mul_f32 v[190:191], v[190:191], v[230:231] op_sel_hi:[1,0]
	v_pk_mul_f32 v[192:193], v[192:193], v[230:231] op_sel_hi:[1,0]
	global_store_dwordx2 v[214:215], v[216:217], off
	v_cvt_pk_bf16_f32 v216, v174, v175
	v_cvt_pk_bf16_f32 v217, v176, v177
	s_waitcnt lgkmcnt(0)
	v_pk_fma_f32 v[192:193], v[224:225], v[192:193], v[228:229]
	v_pk_fma_f32 v[190:191], v[222:223], v[190:191], v[226:227]
	global_store_dwordx2 v[214:215], v[216:217], off offset:512
	v_cvt_pk_bf16_f32 v216, v194, v195
	v_cvt_pk_bf16_f32 v217, v196, v197
	global_store_dwordx2 v[214:215], v[216:217], off offset:1024
	v_cvt_pk_bf16_f32 v216, v190, v191
	v_cvt_pk_bf16_f32 v217, v192, v193
	global_store_dwordx2 v[214:215], v[216:217], off offset:1536
	v_fma_f32 v213, v182, v162, 0
	v_fma_f32 v214, v183, v163, 0
	v_fmac_f32_e32 v213, v184, v164
	v_fmac_f32_e32 v214, v185, v165
	v_fmac_f32_e32 v213, v174, v158
	v_fmac_f32_e32 v214, v175, v159
	v_fmac_f32_e32 v213, v176, v160
	v_fmac_f32_e32 v214, v177, v161
	v_fmac_f32_e32 v213, v194, v154
	v_fmac_f32_e32 v214, v195, v155
	v_fmac_f32_e32 v213, v196, v156
	v_fmac_f32_e32 v214, v197, v157
	v_fmac_f32_e32 v213, v190, v150
	v_fmac_f32_e32 v214, v191, v151
	v_fmac_f32_e32 v213, v192, v152
	v_fmac_f32_e32 v214, v193, v153
	v_add_f32_e32 v213, v213, v214
	v_fma_f32 v214, v182, v146, 0
	v_fma_f32 v215, v183, v147, 0
	v_fmac_f32_e32 v214, v184, v148
	v_fmac_f32_e32 v215, v185, v149
	v_fmac_f32_e32 v214, v174, v142
	v_fmac_f32_e32 v215, v175, v143
	v_fmac_f32_e32 v214, v176, v144
	v_fmac_f32_e32 v215, v177, v145
	v_fmac_f32_e32 v214, v194, v138
	v_fmac_f32_e32 v215, v195, v139
	v_fmac_f32_e32 v214, v196, v140
	v_fmac_f32_e32 v215, v197, v141
	v_fmac_f32_e32 v214, v190, v134
	v_fmac_f32_e32 v215, v191, v135
	v_fmac_f32_e32 v214, v192, v136
	v_fmac_f32_e32 v215, v193, v137
	v_add_f32_e32 v214, v214, v215
	v_fma_f32 v216, v183, v131, 0
	v_fmac_f32_e32 v216, v185, v133
	v_add_f32_dpp v214, v214, v214 quad_perm:[1,0,3,2] row_mask:0xf bank_mask:0xf bound_ctrl:1
	v_fmac_f32_e32 v216, v175, v127
	v_fmac_f32_e32 v216, v177, v129
	v_add_f32_dpp v214, v214, v214 quad_perm:[2,3,0,1] row_mask:0xf bank_mask:0xf bound_ctrl:1
	v_fmac_f32_e32 v216, v195, v123
	v_fmac_f32_e32 v216, v197, v125
	v_add_f32_dpp v214, v214, v214 row_half_mirror row_mask:0xf bank_mask:0xf bound_ctrl:1
	v_fmac_f32_e32 v216, v191, v119
	v_fmac_f32_e32 v216, v193, v121
	v_add_f32_dpp v215, v214, v214 row_mirror row_mask:0xf bank_mask:0xf bound_ctrl:1
	v_fma_f32 v214, v182, v130, 0
	v_fmac_f32_e32 v214, v184, v132
	v_fmac_f32_e32 v214, v174, v126
	v_fmac_f32_e32 v214, v176, v128
	v_fmac_f32_e32 v214, v194, v122
	v_fmac_f32_e32 v214, v196, v124
	v_fmac_f32_e32 v214, v190, v118
	v_fmac_f32_e32 v214, v192, v120
	v_add_f32_e32 v214, v214, v216
	v_fma_f32 v216, v183, v115, 0
	v_fmac_f32_e32 v216, v185, v117
	v_add_f32_dpp v214, v214, v214 quad_perm:[1,0,3,2] row_mask:0xf bank_mask:0xf bound_ctrl:1
	v_fmac_f32_e32 v216, v175, v111
	v_fmac_f32_e32 v216, v177, v113
	v_add_f32_dpp v214, v214, v214 quad_perm:[2,3,0,1] row_mask:0xf bank_mask:0xf bound_ctrl:1
	v_fmac_f32_e32 v216, v195, v107
	v_fmac_f32_e32 v216, v197, v109
	v_add_f32_dpp v214, v214, v214 row_half_mirror row_mask:0xf bank_mask:0xf bound_ctrl:1
	v_fmac_f32_e32 v216, v191, v103
	v_fmac_f32_e32 v216, v193, v105
	v_add_f32_dpp v217, v214, v214 row_mirror row_mask:0xf bank_mask:0xf bound_ctrl:1
	v_fma_f32 v214, v182, v114, 0
	v_fmac_f32_e32 v214, v184, v116
	v_fmac_f32_e32 v214, v174, v110
	v_fmac_f32_e32 v214, v176, v112
	v_fmac_f32_e32 v214, v194, v106
	v_fmac_f32_e32 v214, v196, v108
	v_fmac_f32_e32 v214, v190, v102
	v_fmac_f32_e32 v214, v192, v104
	v_add_f32_e32 v214, v214, v216
	v_fma_f32 v216, v183, v99, 0
	v_fmac_f32_e32 v216, v185, v101
	v_add_f32_dpp v214, v214, v214 quad_perm:[1,0,3,2] row_mask:0xf bank_mask:0xf bound_ctrl:1
	v_fmac_f32_e32 v216, v175, v95
	v_fmac_f32_e32 v216, v177, v97
	v_add_f32_dpp v214, v214, v214 quad_perm:[2,3,0,1] row_mask:0xf bank_mask:0xf bound_ctrl:1
	v_fmac_f32_e32 v216, v195, v91
	v_fmac_f32_e32 v216, v197, v93
	v_add_f32_dpp v214, v214, v214 row_half_mirror row_mask:0xf bank_mask:0xf bound_ctrl:1
	v_fmac_f32_e32 v216, v191, v87
	v_fmac_f32_e32 v216, v193, v89
	v_add_f32_dpp v219, v214, v214 row_mirror row_mask:0xf bank_mask:0xf bound_ctrl:1
	v_fma_f32 v214, v182, v98, 0
	v_fmac_f32_e32 v214, v184, v100
	v_fmac_f32_e32 v214, v174, v94
	v_fmac_f32_e32 v214, v176, v96
	v_fmac_f32_e32 v214, v194, v90
	v_fmac_f32_e32 v214, v196, v92
	v_fmac_f32_e32 v214, v190, v86
	v_fmac_f32_e32 v214, v192, v88
	v_add_f32_e32 v214, v214, v216
	v_fma_f32 v216, v183, v83, 0
	v_fmac_f32_e32 v216, v185, v85
	v_add_f32_dpp v214, v214, v214 quad_perm:[1,0,3,2] row_mask:0xf bank_mask:0xf bound_ctrl:1
	v_fmac_f32_e32 v216, v175, v79
	v_fmac_f32_e32 v216, v177, v81
	v_add_f32_dpp v214, v214, v214 quad_perm:[2,3,0,1] row_mask:0xf bank_mask:0xf bound_ctrl:1
	v_fmac_f32_e32 v216, v195, v75
	v_fmac_f32_e32 v216, v197, v77
	v_add_f32_dpp v214, v214, v214 row_half_mirror row_mask:0xf bank_mask:0xf bound_ctrl:1
	v_fmac_f32_e32 v216, v191, v71
	v_fmac_f32_e32 v216, v193, v73
	v_add_f32_dpp v221, v214, v214 row_mirror row_mask:0xf bank_mask:0xf bound_ctrl:1
	v_fma_f32 v214, v182, v82, 0
	v_fmac_f32_e32 v214, v184, v84
	v_fmac_f32_e32 v214, v174, v78
	v_fmac_f32_e32 v214, v176, v80
	v_fmac_f32_e32 v214, v194, v74
	v_fmac_f32_e32 v214, v196, v76
	v_fmac_f32_e32 v214, v190, v70
	v_fmac_f32_e32 v214, v192, v72
	v_add_f32_e32 v214, v214, v216
	v_fma_f32 v216, v183, v67, 0
	v_fmac_f32_e32 v216, v185, v69
	v_add_f32_dpp v214, v214, v214 quad_perm:[1,0,3,2] row_mask:0xf bank_mask:0xf bound_ctrl:1
	v_fmac_f32_e32 v216, v175, v63
	v_fmac_f32_e32 v216, v177, v65
	v_add_f32_dpp v214, v214, v214 quad_perm:[2,3,0,1] row_mask:0xf bank_mask:0xf bound_ctrl:1
	v_fmac_f32_e32 v216, v195, v59
	v_fmac_f32_e32 v216, v197, v61
	v_add_f32_dpp v214, v214, v214 row_half_mirror row_mask:0xf bank_mask:0xf bound_ctrl:1
	v_fmac_f32_e32 v216, v191, v55
	v_fmac_f32_e32 v216, v193, v57
	v_add_f32_dpp v223, v214, v214 row_mirror row_mask:0xf bank_mask:0xf bound_ctrl:1
	v_fma_f32 v214, v182, v66, 0
	v_fmac_f32_e32 v214, v184, v68
	v_fmac_f32_e32 v214, v174, v62
	v_fmac_f32_e32 v214, v176, v64
	v_fmac_f32_e32 v214, v194, v58
	v_fmac_f32_e32 v214, v196, v60
	v_fmac_f32_e32 v214, v190, v54
	v_fmac_f32_e32 v214, v192, v56
	v_add_f32_e32 v214, v214, v216
	v_fma_f32 v216, v183, v51, 0
	v_fmac_f32_e32 v216, v185, v53
	v_add_f32_dpp v214, v214, v214 quad_perm:[1,0,3,2] row_mask:0xf bank_mask:0xf bound_ctrl:1
	v_fmac_f32_e32 v216, v175, v47
	v_fmac_f32_e32 v216, v177, v49
	v_add_f32_dpp v214, v214, v214 quad_perm:[2,3,0,1] row_mask:0xf bank_mask:0xf bound_ctrl:1
	v_fmac_f32_e32 v216, v195, v43
	v_fmac_f32_e32 v216, v197, v45
	v_add_f32_dpp v214, v214, v214 row_half_mirror row_mask:0xf bank_mask:0xf bound_ctrl:1
	v_fmac_f32_e32 v216, v191, v39
	v_fmac_f32_e32 v216, v193, v41
	v_add_f32_dpp v225, v214, v214 row_mirror row_mask:0xf bank_mask:0xf bound_ctrl:1
	v_fma_f32 v214, v182, v50, 0
	v_fmac_f32_e32 v214, v184, v52
	v_fmac_f32_e32 v214, v174, v46
	v_fmac_f32_e32 v214, v176, v48
	v_fmac_f32_e32 v214, v194, v42
	v_fmac_f32_e32 v214, v196, v44
	v_fmac_f32_e32 v214, v190, v38
	v_fmac_f32_e32 v214, v192, v40
	v_add_f32_e32 v214, v214, v216
	v_add_f32_dpp v213, v213, v213 quad_perm:[1,0,3,2] row_mask:0xf bank_mask:0xf bound_ctrl:1
	ds_bpermute_b32 v218, v200, v215
	v_add_f32_dpp v214, v214, v214 quad_perm:[1,0,3,2] row_mask:0xf bank_mask:0xf bound_ctrl:1
	v_add_f32_dpp v213, v213, v213 quad_perm:[2,3,0,1] row_mask:0xf bank_mask:0xf bound_ctrl:1
	ds_bpermute_b32 v220, v200, v217
	v_add_f32_dpp v214, v214, v214 quad_perm:[2,3,0,1] row_mask:0xf bank_mask:0xf bound_ctrl:1
	v_add_f32_dpp v213, v213, v213 row_half_mirror row_mask:0xf bank_mask:0xf bound_ctrl:1
	ds_bpermute_b32 v222, v200, v219
	v_add_f32_dpp v214, v214, v214 row_half_mirror row_mask:0xf bank_mask:0xf bound_ctrl:1
	v_add_f32_dpp v213, v213, v213 row_mirror row_mask:0xf bank_mask:0xf bound_ctrl:1
	ds_bpermute_b32 v216, v200, v213
	v_add_f32_dpp v227, v214, v214 row_mirror row_mask:0xf bank_mask:0xf bound_ctrl:1
	ds_bpermute_b32 v224, v200, v221
	ds_bpermute_b32 v226, v200, v223
	ds_bpermute_b32 v228, v200, v225
	ds_bpermute_b32 v229, v200, v227
	s_waitcnt lgkmcnt(4)
	v_add_f32_e32 v213, v213, v216
	v_add_f32_e32 v215, v215, v218
	v_add_f32_e32 v217, v217, v220
	v_add_f32_e32 v219, v219, v222
	s_waitcnt lgkmcnt(3)
	v_add_f32_e32 v221, v221, v224
	s_waitcnt lgkmcnt(2)
	v_add_f32_e32 v223, v223, v226
	s_waitcnt lgkmcnt(1)
	v_add_f32_e32 v225, v225, v228
	s_waitcnt lgkmcnt(0)
	v_add_f32_e32 v227, v227, v229
	ds_bpermute_b32 v214, v203, v213
	ds_bpermute_b32 v216, v203, v215
	ds_bpermute_b32 v218, v203, v217
	ds_bpermute_b32 v220, v203, v219
	ds_bpermute_b32 v222, v203, v221
	ds_bpermute_b32 v224, v203, v223
	ds_bpermute_b32 v226, v203, v225
	ds_bpermute_b32 v228, v203, v227
	s_and_saveexec_b64 s[14:15], s[2:3]
	s_cbranch_execz .LBB0_77
	s_waitcnt lgkmcnt(0)
	v_add_f32_e32 v227, v227, v228
	v_add_f32_e32 v225, v225, v226
	v_add_f32_e32 v226, v37, v227
	v_mul_f32_e64 v227, |v226|, s30
	v_exp_f32_e32 v227, v227
	v_add_f32_e32 v221, v221, v222
	v_add_f32_e32 v222, v219, v220
	v_add_f32_e32 v213, v213, v214
	v_add_f32_e32 v219, 1.0, v227
	v_cmp_gt_f32_e32 vcc, s31, v219
	v_add_f32_e32 v227, v215, v216
	v_add_f32_e32 v216, v36, v225
	v_cndmask_b32_e64 v220, 0, 32, vcc
	v_ldexp_f32 v219, v219, v220
	v_log_f32_e32 v219, v219
	v_mul_f32_e64 v215, |v216|, s30
	v_exp_f32_e32 v215, v215
	v_add_f32_e32 v223, v223, v224
	v_mul_f32_e32 v214, 0x3f317217, v219
	v_fma_f32 v214, v219, s33, -v214
	v_fmac_f32_e32 v214, 0x3377d1cf, v219
	v_fmac_f32_e32 v214, 0x3f317217, v219
	v_cmp_lt_f32_e64 s[4:5], |v219|, s34
	v_add_f32_e32 v215, 1.0, v215
	v_add_f32_e32 v224, v217, v218
	v_cndmask_b32_e64 v214, v219, v214, s[4:5]
	v_cmp_gt_f32_e64 s[4:5], s31, v215
	v_add_f32_e32 v220, v35, v223
	v_mul_f32_e64 v219, |v220|, s30
	v_cndmask_b32_e64 v217, 0, 32, s[4:5]
	v_ldexp_f32 v215, v215, v217
	v_log_f32_e32 v218, v215
	v_cndmask_b32_e32 v215, 0, v212, vcc
	v_sub_f32_e32 v215, v214, v215
	v_exp_f32_e32 v219, v219
	v_mul_f32_e32 v214, 0x3f317217, v218
	v_fma_f32 v214, v218, s33, -v214
	v_fmac_f32_e32 v214, 0x3377d1cf, v218
	v_fmac_f32_e32 v214, 0x3f317217, v218
	v_cmp_lt_f32_e64 vcc, |v218|, s34
	v_add_f32_e32 v223, v34, v221
	v_mul_f32_e64 v221, |v223|, s30
	v_cndmask_b32_e32 v214, v218, v214, vcc
	v_add_f32_e32 v218, 1.0, v219
	v_cmp_gt_f32_e32 vcc, s31, v218
	v_exp_f32_e32 v221, v221
	v_mul_f32_e32 v213, 0xbfb8aa3b, v213
	v_cndmask_b32_e64 v219, 0, 32, vcc
	v_ldexp_f32 v218, v218, v219
	v_log_f32_e32 v218, v218
	v_cndmask_b32_e64 v219, 0, v212, s[4:5]
	v_sub_f32_e32 v214, v214, v219
	v_exp_f32_e32 v213, v213
	v_mul_f32_e32 v219, 0x3f317217, v218
	v_fma_f32 v219, v218, s33, -v219
	v_fmac_f32_e32 v219, 0x3377d1cf, v218
	v_fmac_f32_e32 v219, 0x3f317217, v218
	v_cmp_lt_f32_e64 s[4:5], |v218|, s34
	v_mul_f32_e32 v222, 0xbfb8aa3b, v222
	v_max_f32_e32 v217, 0, v226
	v_cndmask_b32_e64 v218, v218, v219, s[4:5]
	v_add_f32_e32 v219, 1.0, v221
	v_cmp_gt_f32_e64 s[4:5], s31, v219
	v_max_f32_e32 v216, 0, v216
	v_exp_f32_e32 v222, v222
	v_cndmask_b32_e64 v221, 0, 32, s[4:5]
	v_ldexp_f32 v219, v219, v221
	v_log_f32_e32 v225, v219
	v_cndmask_b32_e32 v219, 0, v212, vcc
	v_sub_f32_e32 v219, v218, v219
	v_max_f32_e32 v221, 0, v220
	v_mul_f32_e32 v218, 0x3f317217, v225
	v_fma_f32 v218, v225, s33, -v218
	v_fmac_f32_e32 v218, 0x3377d1cf, v225
	v_fmac_f32_e32 v218, 0x3f317217, v225
	v_cmp_lt_f32_e64 vcc, |v225|, s34
	v_cndmask_b32_e64 v220, 0, v212, s[4:5]
	v_pk_add_f32 v[214:215], v[216:217], v[214:215]
	v_cndmask_b32_e32 v218, v225, v218, vcc
	v_sub_f32_e32 v218, v218, v220
	v_max_f32_e32 v220, 0, v223
	v_mul_f32_e32 v223, 0xbfb8aa3b, v224
	v_mul_f32_e32 v224, 0xbfb8aa3b, v227
	v_exp_f32_e32 v224, v224
	v_exp_f32_e32 v223, v223
	v_pk_add_f32 v[218:219], v[220:221], v[218:219]
	v_add_f32_e32 v213, 1.0, v213
	v_pk_mul_f32 v[216:217], v[214:215], s[10:11]
	v_pk_mul_f32 v[214:215], v[218:219], s[8:9] neg_lo:[0,1] neg_hi:[0,1]
	v_rcp_f32_e32 v218, v213
	v_add_f32_e32 v213, 1.0, v224
	v_rcp_f32_e32 v219, v213
	v_add_f32_e32 v213, 1.0, v223
	v_rcp_f32_e32 v220, v213
	v_add_f32_e32 v213, 1.0, v222
	s_lshl_b64 s[4:5], s[12:13], 4
	v_rcp_f32_e32 v221, v213
	s_add_u32 s12, s24, s4
	s_addc_u32 s13, s25, s5
	s_add_u32 s4, s26, s4
	s_addc_u32 s5, s27, s5
	global_store_dwordx4 v201, v[218:221], s[12:13]
	global_store_dwordx4 v201, v[214:217], s[4:5]
	s_branch .LBB0_77
.LBB0_100:
	s_waitcnt vmcnt(0)
.LBB0_116:
	v_readlane_b32 s63, v254, 2
